# non-temporal hints on read-once streams (x inputs, f32 weights in prep, chunk states in scan) and on the final Y stores
# speedup vs baseline: 1.0431x; 1.0188x over previous
.LBB0_66:
	v_ashrrev_i32_e32 v9, 31, v8
	v_lshlrev_b64 v[10:11], 6, v[8:9]
	v_lshl_add_u64 v[22:23], s[2:3], 0, v[10:11]
	global_load_dwordx4 v[10:13], v[22:23], off
	global_load_dwordx4 v[14:17], v[22:23], off offset:16
	v_lshlrev_b64 v[18:19], 11, v[8:9]
	v_lshl_add_u64 v[30:31], v[4:5], 0, v[18:19]
	global_load_dwordx2 v[32:33], v[30:31], off
	global_load_dwordx4 v[18:21], v[22:23], off offset:32
	s_nop 0
	global_load_dwordx4 v[22:25], v[22:23], off offset:48
	s_nop 0
	global_load_dwordx4 v[26:29], v[2:3], off
	v_lshlrev_b64 v[34:35], 12, v[8:9]
	v_lshl_add_u64 v[34:35], v[6:7], 0, v[34:35]
	s_add_i32 s6, s6, s4
	s_cmpk_gt_i32 s6, 0x83f
	v_add_u32_e32 v8, s5, v8
	s_waitcnt vmcnt(4)
	v_pk_add_f32 v[12:13], v[12:13], v[16:17]
	v_pk_add_f32 v[10:11], v[10:11], v[14:15]
	s_waitcnt vmcnt(2)
	v_pk_add_f32 v[12:13], v[12:13], v[20:21]
	v_pk_add_f32 v[10:11], v[10:11], v[18:19]
	s_waitcnt vmcnt(1)
	v_pk_add_f32 v[12:13], v[12:13], v[24:25]
	v_pk_add_f32 v[10:11], v[10:11], v[22:23]
	v_lshlrev_b32_e32 v14, 16, v32
	v_pk_mov_b32 v[16:17], v[10:11], v[12:13] op_sel:[1,0]
	v_mov_b32_e32 v11, v13
	v_pk_add_f32 v[10:11], v[16:17], v[10:11]
	v_and_b32_e32 v15, 0xffff0000, v32
	v_add_f32_e32 v9, v10, v11
	v_fmamk_f32 v9, v9, 0x3a800000, v238
	v_mul_f32_e32 v10, 0x4b800000, v9
	v_cmp_gt_f32_e32 vcc, s34, v9
	v_and_b32_e32 v11, 0xffff0000, v33
	s_nop 0
	v_cndmask_b32_e32 v9, v9, v10, vcc
	v_rsq_f32_e32 v9, v9
	v_lshlrev_b32_e32 v10, 16, v33
	v_mul_f32_e32 v12, 0x45800000, v9
	v_cndmask_b32_e32 v16, v9, v12, vcc
	v_pk_mul_f32 v[12:13], v[16:17], v[14:15] op_sel_hi:[0,1]
	v_pk_mul_f32 v[14:15], v[16:17], v[10:11] op_sel_hi:[0,1]
	s_waitcnt vmcnt(0)
	v_pk_mul_f32 v[10:11], v[26:27], v[12:13]
	v_pk_mul_f32 v[12:13], v[28:29], v[14:15]
	global_store_dwordx4 v[34:35], v[10:13], off nt
	global_load_dwordx2 v[14:15], v[30:31], off offset:512
	s_nop 0
	global_load_dwordx4 v[10:13], v[2:3], off offset:1024
	s_waitcnt vmcnt(1)
	v_lshlrev_b32_e32 v18, 16, v14
	v_and_b32_e32 v19, 0xffff0000, v14
	v_lshlrev_b32_e32 v14, 16, v15
	v_and_b32_e32 v15, 0xffff0000, v15
	v_pk_mul_f32 v[18:19], v[16:17], v[18:19] op_sel_hi:[0,1]
	v_pk_mul_f32 v[14:15], v[16:17], v[14:15] op_sel_hi:[0,1]
	s_waitcnt vmcnt(0)
	v_pk_mul_f32 v[10:11], v[10:11], v[18:19]
	v_pk_mul_f32 v[12:13], v[12:13], v[14:15]
	global_store_dwordx4 v[34:35], v[10:13], off offset:1024 nt
	global_load_dwordx2 v[14:15], v[30:31], off offset:1024
	s_nop 0
	global_load_dwordx4 v[10:13], v[2:3], off offset:2048
	s_waitcnt vmcnt(1)
	v_lshlrev_b32_e32 v18, 16, v14
	v_and_b32_e32 v19, 0xffff0000, v14
	v_lshlrev_b32_e32 v14, 16, v15
	v_and_b32_e32 v15, 0xffff0000, v15
	v_pk_mul_f32 v[18:19], v[16:17], v[18:19] op_sel_hi:[0,1]
	v_pk_mul_f32 v[14:15], v[16:17], v[14:15] op_sel_hi:[0,1]
	s_waitcnt vmcnt(0)
	v_pk_mul_f32 v[10:11], v[10:11], v[18:19]
	v_pk_mul_f32 v[12:13], v[12:13], v[14:15]
	global_store_dwordx4 v[34:35], v[10:13], off offset:2048 nt
	global_load_dwordx2 v[14:15], v[30:31], off offset:1536
	s_nop 0
	global_load_dwordx4 v[10:13], v[2:3], off offset:3072
	s_waitcnt vmcnt(1)
	v_lshlrev_b32_e32 v18, 16, v14
	v_and_b32_e32 v19, 0xffff0000, v14
	v_lshlrev_b32_e32 v14, 16, v15
	v_and_b32_e32 v15, 0xffff0000, v15
	v_pk_mul_f32 v[18:19], v[16:17], v[18:19] op_sel_hi:[0,1]
	v_pk_mul_f32 v[14:15], v[16:17], v[14:15] op_sel_hi:[0,1]
	s_waitcnt vmcnt(0)
	v_pk_mul_f32 v[10:11], v[10:11], v[18:19]
	v_pk_mul_f32 v[12:13], v[12:13], v[14:15]
	global_store_dwordx4 v[34:35], v[10:13], off offset:3072 nt
	s_cbranch_scc0 .LBB0_66

.LBB0_140:
	v_add_u32_e32 v42, s19, v44
	v_ashrrev_i32_e32 v43, 31, v42
	v_mul_lo_u32 v6, s0, v43
	v_mul_lo_u32 v7, s1, v42
	v_mad_u64_u32 v[2:3], s[12:13], s0, v42, 0
	v_add3_u32 v3, v3, v6, v7
	v_add_u32_e32 v6, 32, v42
	v_ashrrev_i32_e32 v7, 31, v6
	v_mul_lo_u32 v8, s0, v7
	v_mul_lo_u32 v9, s1, v6
	v_mad_u64_u32 v[6:7], s[12:13], s0, v6, 0
	v_lshl_add_u64 v[2:3], v[2:3], 2, v[4:5]
	v_add3_u32 v7, v7, v8, v9
	v_lshl_add_u64 v[6:7], v[6:7], 2, v[4:5]
	global_load_dwordx4 v[30:33], v[2:3], off nt
	global_load_dwordx4 v[22:25], v[6:7], off nt
	v_add_u32_e32 v2, 64, v42
	v_ashrrev_i32_e32 v3, 31, v2
	v_mul_lo_u32 v6, s0, v3
	v_mul_lo_u32 v7, s1, v2
	v_mad_u64_u32 v[2:3], s[12:13], s0, v2, 0
	v_add3_u32 v3, v3, v6, v7
	v_add_u32_e32 v6, 0x60, v42
	v_ashrrev_i32_e32 v7, 31, v6
	v_mul_lo_u32 v8, s0, v7
	v_mul_lo_u32 v9, s1, v6
	v_mad_u64_u32 v[6:7], s[12:13], s0, v6, 0
	v_lshl_add_u64 v[2:3], v[2:3], 2, v[4:5]
	v_add3_u32 v7, v7, v8, v9
	v_lshl_add_u64 v[6:7], v[6:7], 2, v[4:5]
	global_load_dwordx4 v[26:29], v[2:3], off nt
	global_load_dwordx4 v[14:17], v[6:7], off nt
	v_add_u32_e32 v2, 0x80, v42
	v_ashrrev_i32_e32 v3, 31, v2
	v_mul_lo_u32 v6, s0, v3
	v_mul_lo_u32 v7, s1, v2
	v_mad_u64_u32 v[2:3], s[12:13], s0, v2, 0
	v_add3_u32 v3, v3, v6, v7
	v_add_u32_e32 v6, 0xa0, v42
	v_ashrrev_i32_e32 v7, 31, v6
	v_mul_lo_u32 v8, s0, v7
	v_mul_lo_u32 v9, s1, v6
	v_mad_u64_u32 v[6:7], s[12:13], s0, v6, 0
	v_add3_u32 v7, v7, v8, v9
	v_lshl_add_u64 v[2:3], v[2:3], 2, v[4:5]
	v_lshl_add_u64 v[6:7], v[6:7], 2, v[4:5]
	global_load_dwordx4 v[18:21], v[2:3], off nt
	s_nop 0
	global_load_dwordx4 v[6:9], v[6:7], off nt
	v_add_u32_e32 v2, 0xc0, v42
	v_ashrrev_i32_e32 v3, 31, v2
	v_mul_lo_u32 v10, s0, v3
	v_mul_lo_u32 v11, s1, v2
	v_mad_u64_u32 v[2:3], s[12:13], s0, v2, 0
	v_add3_u32 v3, v3, v10, v11
	v_add_u32_e32 v10, 0xe0, v42
	v_ashrrev_i32_e32 v11, 31, v10
	v_mul_lo_u32 v12, s0, v11
	v_mul_lo_u32 v13, s1, v10
	v_mad_u64_u32 v[10:11], s[0:1], s0, v10, 0
	v_add3_u32 v11, v11, v12, v13
	v_lshl_add_u64 v[2:3], v[2:3], 2, v[4:5]
	v_lshl_add_u64 v[4:5], v[10:11], 2, v[4:5]
	global_load_dwordx4 v[10:13], v[2:3], off nt
	s_nop 0
	global_load_dwordx4 v[2:5], v[4:5], off nt
	s_cmp_lt_i32 s18, 2
	s_mov_b64 s[12:13], -1
	s_waitcnt vmcnt(0)
	s_barrier
	s_cbranch_scc1 .LBB0_143
	s_mov_b64 s[12:13], 0
	s_cmp_eq_u32 s18, 2
	s_mov_b64 s[0:1], 0
	s_cbranch_scc0 .LBB0_143
	s_lshl_b32 s0, s8, 10
	s_ashr_i32 s1, s0, 31
	s_mov_b64 s[22:23], s[74:75]
	s_mov_b32 s9, s60
	v_readlane_b32 s60, v252, 5
	s_lshl_b64 s[0:1], s[0:1], 2
	v_readlane_b32 s68, v252, 13
	v_readlane_b32 s69, v252, 14
	v_readlane_b32 s72, v252, 17
	v_readlane_b32 s73, v252, 18
	v_readlane_b32 s74, v252, 19
	v_readlane_b32 s66, v252, 11
	v_readlane_b32 s67, v252, 12
	v_readlane_b32 s70, v252, 15
	v_readlane_b32 s71, v252, 16
	v_readlane_b32 s75, v252, 20
	v_readlane_b32 s72, v252, 44
	v_readlane_b32 s68, v252, 38
	s_add_u32 s0, s74, s0
	s_mov_b32 s60, s9
	v_readlane_b32 s73, v252, 45
	s_mov_b64 s[70:71], s[48:49]
	v_readlane_b32 s69, v252, 39
	s_mov_b64 s[66:67], s[50:51]
	s_addc_u32 s1, s75, s1
	s_mov_b64 s[74:75], s[22:23]
	v_readlane_b32 s61, v252, 6
	v_readlane_b32 s62, v252, 7
	v_readlane_b32 s63, v252, 8
	v_readlane_b32 s64, v252, 9
	v_readlane_b32 s65, v252, 10

.LBB0_221:
	v_add_u32_e32 v42, s16, v44
	v_ashrrev_i32_e32 v43, 31, v42
	v_mul_lo_u32 v6, s0, v43
	v_mul_lo_u32 v7, s1, v42
	v_mad_u64_u32 v[2:3], s[10:11], s0, v42, 0
	v_add3_u32 v3, v3, v6, v7
	v_add_u32_e32 v6, 32, v42
	v_ashrrev_i32_e32 v7, 31, v6
	v_mul_lo_u32 v8, s0, v7
	v_mul_lo_u32 v9, s1, v6
	v_mad_u64_u32 v[6:7], s[10:11], s0, v6, 0
	v_lshl_add_u64 v[2:3], v[2:3], 2, v[4:5]
	v_add3_u32 v7, v7, v8, v9
	v_lshl_add_u64 v[6:7], v[6:7], 2, v[4:5]
	global_load_dwordx4 v[30:33], v[2:3], off nt
	global_load_dwordx4 v[22:25], v[6:7], off nt
	v_add_u32_e32 v2, 64, v42
	v_ashrrev_i32_e32 v3, 31, v2
	v_mul_lo_u32 v6, s0, v3
	v_mul_lo_u32 v7, s1, v2
	v_mad_u64_u32 v[2:3], s[10:11], s0, v2, 0
	v_add3_u32 v3, v3, v6, v7
	v_add_u32_e32 v6, 0x60, v42
	v_ashrrev_i32_e32 v7, 31, v6
	v_mul_lo_u32 v8, s0, v7
	v_mul_lo_u32 v9, s1, v6
	v_mad_u64_u32 v[6:7], s[10:11], s0, v6, 0
	v_lshl_add_u64 v[2:3], v[2:3], 2, v[4:5]
	v_add3_u32 v7, v7, v8, v9
	v_lshl_add_u64 v[6:7], v[6:7], 2, v[4:5]
	global_load_dwordx4 v[26:29], v[2:3], off nt
	global_load_dwordx4 v[14:17], v[6:7], off nt
	v_add_u32_e32 v2, 0x80, v42
	v_ashrrev_i32_e32 v3, 31, v2
	v_mul_lo_u32 v6, s0, v3
	v_mul_lo_u32 v7, s1, v2
	v_mad_u64_u32 v[2:3], s[10:11], s0, v2, 0
	v_add3_u32 v3, v3, v6, v7
	v_add_u32_e32 v6, 0xa0, v42
	v_ashrrev_i32_e32 v7, 31, v6
	v_mul_lo_u32 v8, s0, v7
	v_mul_lo_u32 v9, s1, v6
	v_mad_u64_u32 v[6:7], s[10:11], s0, v6, 0
	v_add3_u32 v7, v7, v8, v9
	v_lshl_add_u64 v[2:3], v[2:3], 2, v[4:5]
	v_lshl_add_u64 v[6:7], v[6:7], 2, v[4:5]
	global_load_dwordx4 v[18:21], v[2:3], off nt
	s_nop 0
	global_load_dwordx4 v[6:9], v[6:7], off nt
	v_add_u32_e32 v2, 0xc0, v42
	v_ashrrev_i32_e32 v3, 31, v2
	v_mul_lo_u32 v10, s0, v3
	v_mul_lo_u32 v11, s1, v2
	v_mad_u64_u32 v[2:3], s[10:11], s0, v2, 0
	v_add3_u32 v3, v3, v10, v11
	v_add_u32_e32 v10, 0xe0, v42
	v_ashrrev_i32_e32 v11, 31, v10
	v_mul_lo_u32 v12, s0, v11
	v_mul_lo_u32 v13, s1, v10
	v_mad_u64_u32 v[10:11], s[0:1], s0, v10, 0
	v_add3_u32 v11, v11, v12, v13
	v_lshl_add_u64 v[2:3], v[2:3], 2, v[4:5]
	v_lshl_add_u64 v[4:5], v[10:11], 2, v[4:5]
	global_load_dwordx4 v[10:13], v[2:3], off nt
	s_nop 0
	global_load_dwordx4 v[2:5], v[4:5], off nt
	s_cmp_lt_i32 s15, 2
	s_mov_b64 s[10:11], -1
	s_waitcnt vmcnt(0)
	s_barrier
	s_cbranch_scc1 .LBB0_224
	s_mov_b64 s[10:11], 0
	s_cmp_eq_u32 s15, 2
	s_mov_b64 s[0:1], 0
	s_cbranch_scc0 .LBB0_224
	s_lshl_b32 s0, s6, 10
	s_ashr_i32 s1, s0, 31
	s_mov_b64 s[18:19], s[74:75]
	s_mov_b32 s7, s60
	v_readlane_b32 s60, v252, 5
	s_lshl_b64 s[0:1], s[0:1], 2
	v_readlane_b32 s68, v252, 13
	v_readlane_b32 s69, v252, 14
	v_readlane_b32 s72, v252, 17
	v_readlane_b32 s73, v252, 18
	v_readlane_b32 s74, v252, 19
	v_readlane_b32 s66, v252, 11
	v_readlane_b32 s67, v252, 12
	v_readlane_b32 s70, v252, 15
	v_readlane_b32 s71, v252, 16
	v_readlane_b32 s75, v252, 20
	v_readlane_b32 s72, v252, 44
	v_readlane_b32 s68, v252, 38
	s_add_u32 s0, s74, s0
	s_mov_b32 s60, s7
	v_readlane_b32 s73, v252, 45
	s_mov_b64 s[70:71], s[48:49]
	v_readlane_b32 s69, v252, 39
	s_mov_b64 s[66:67], s[50:51]
	s_addc_u32 s1, s75, s1
	s_mov_b64 s[74:75], s[18:19]
	v_readlane_b32 s61, v252, 6
	v_readlane_b32 s62, v252, 7
	v_readlane_b32 s63, v252, 8
	v_readlane_b32 s64, v252, 9
	v_readlane_b32 s65, v252, 10

.LBB0_439:
	v_ashrrev_i32_e32 v134, 15, v132
	v_and_b32_e32 v211, 0x7fff, v132
	v_lshlrev_b32_e32 v130, 6, v134
	v_lshlrev_b32_e32 v190, 2, v211
	v_ashrrev_i32_e32 v131, 31, v130
	v_lshl_add_u64 v[98:99], s[22:23], 0, v[190:191]
	v_lshlrev_b64 v[2:3], 17, v[130:131]
	v_or_b32_e32 v128, 1, v130
	v_lshl_add_u64 v[2:3], v[98:99], 0, v[2:3]
	v_ashrrev_i32_e32 v129, 31, v128
	global_load_dword v210, v[2:3], off nt
	v_lshlrev_b64 v[2:3], 17, v[128:129]
	v_or_b32_e32 v126, 2, v130
	v_lshl_add_u64 v[2:3], v[98:99], 0, v[2:3]
	v_ashrrev_i32_e32 v127, 31, v126
	global_load_dword v209, v[2:3], off nt
	v_lshlrev_b64 v[2:3], 17, v[126:127]
	v_or_b32_e32 v124, 3, v130
	v_lshl_add_u64 v[2:3], v[98:99], 0, v[2:3]
	v_ashrrev_i32_e32 v125, 31, v124
	global_load_dword v207, v[2:3], off nt
	v_lshlrev_b64 v[2:3], 17, v[124:125]
	v_or_b32_e32 v122, 4, v130
	v_lshl_add_u64 v[2:3], v[98:99], 0, v[2:3]
	v_ashrrev_i32_e32 v123, 31, v122
	global_load_dword v206, v[2:3], off nt
	v_lshlrev_b64 v[2:3], 17, v[122:123]
	v_or_b32_e32 v120, 5, v130
	v_lshl_add_u64 v[2:3], v[98:99], 0, v[2:3]
	v_ashrrev_i32_e32 v121, 31, v120
	global_load_dword v205, v[2:3], off nt
	v_lshlrev_b64 v[2:3], 17, v[120:121]
	v_or_b32_e32 v118, 6, v130
	v_lshl_add_u64 v[2:3], v[98:99], 0, v[2:3]
	v_ashrrev_i32_e32 v119, 31, v118
	global_load_dword v204, v[2:3], off nt
	v_lshlrev_b64 v[2:3], 17, v[118:119]
	v_or_b32_e32 v116, 7, v130
	v_lshl_add_u64 v[2:3], v[98:99], 0, v[2:3]
	v_ashrrev_i32_e32 v117, 31, v116
	global_load_dword v203, v[2:3], off nt
	v_lshlrev_b64 v[2:3], 17, v[116:117]
	v_or_b32_e32 v114, 8, v130
	v_lshl_add_u64 v[2:3], v[98:99], 0, v[2:3]
	v_ashrrev_i32_e32 v115, 31, v114
	global_load_dword v199, v[2:3], off nt
	v_lshlrev_b64 v[2:3], 17, v[114:115]
	v_or_b32_e32 v112, 9, v130
	v_lshl_add_u64 v[2:3], v[98:99], 0, v[2:3]
	v_ashrrev_i32_e32 v113, 31, v112
	global_load_dword v189, v[2:3], off nt
	v_lshlrev_b64 v[2:3], 17, v[112:113]
	v_or_b32_e32 v110, 10, v130
	v_lshl_add_u64 v[2:3], v[98:99], 0, v[2:3]
	v_ashrrev_i32_e32 v111, 31, v110
	global_load_dword v188, v[2:3], off nt
	v_lshlrev_b64 v[2:3], 17, v[110:111]
	v_or_b32_e32 v108, 11, v130
	v_lshl_add_u64 v[2:3], v[98:99], 0, v[2:3]
	v_ashrrev_i32_e32 v109, 31, v108
	global_load_dword v187, v[2:3], off nt
	v_lshlrev_b64 v[2:3], 17, v[108:109]
	v_or_b32_e32 v106, 12, v130
	v_lshl_add_u64 v[2:3], v[98:99], 0, v[2:3]
	v_ashrrev_i32_e32 v107, 31, v106
	global_load_dword v186, v[2:3], off nt
	v_lshlrev_b64 v[2:3], 17, v[106:107]
	v_or_b32_e32 v104, 13, v130
	v_lshl_add_u64 v[2:3], v[98:99], 0, v[2:3]
	v_ashrrev_i32_e32 v105, 31, v104
	global_load_dword v185, v[2:3], off nt
	v_lshlrev_b64 v[2:3], 17, v[104:105]
	v_or_b32_e32 v102, 14, v130
	v_lshl_add_u64 v[2:3], v[98:99], 0, v[2:3]
	v_ashrrev_i32_e32 v103, 31, v102
	global_load_dword v184, v[2:3], off nt
	v_lshlrev_b64 v[2:3], 17, v[102:103]
	v_or_b32_e32 v100, 15, v130
	v_lshl_add_u64 v[2:3], v[98:99], 0, v[2:3]
	v_ashrrev_i32_e32 v101, 31, v100
	global_load_dword v183, v[2:3], off nt
	v_lshlrev_b64 v[2:3], 17, v[100:101]
	v_or_b32_e32 v96, 16, v130
	v_lshl_add_u64 v[2:3], v[98:99], 0, v[2:3]
	v_ashrrev_i32_e32 v97, 31, v96
	global_load_dword v182, v[2:3], off nt
	v_lshlrev_b64 v[2:3], 17, v[96:97]
	v_or_b32_e32 v94, 17, v130
	v_lshl_add_u64 v[2:3], v[98:99], 0, v[2:3]
	v_ashrrev_i32_e32 v95, 31, v94
	global_load_dword v181, v[2:3], off nt
	v_lshlrev_b64 v[2:3], 17, v[94:95]
	v_or_b32_e32 v92, 18, v130
	v_lshl_add_u64 v[2:3], v[98:99], 0, v[2:3]
	v_ashrrev_i32_e32 v93, 31, v92
	global_load_dword v180, v[2:3], off nt
	v_lshlrev_b64 v[2:3], 17, v[92:93]
	v_or_b32_e32 v90, 19, v130
	v_lshl_add_u64 v[2:3], v[98:99], 0, v[2:3]
	v_ashrrev_i32_e32 v91, 31, v90
	global_load_dword v179, v[2:3], off nt
	v_lshlrev_b64 v[2:3], 17, v[90:91]
	v_or_b32_e32 v88, 20, v130
	v_lshl_add_u64 v[2:3], v[98:99], 0, v[2:3]
	v_ashrrev_i32_e32 v89, 31, v88
	global_load_dword v178, v[2:3], off nt
	v_lshlrev_b64 v[2:3], 17, v[88:89]
	v_or_b32_e32 v86, 21, v130
	v_lshl_add_u64 v[2:3], v[98:99], 0, v[2:3]
	v_ashrrev_i32_e32 v87, 31, v86
	global_load_dword v177, v[2:3], off nt
	v_lshlrev_b64 v[2:3], 17, v[86:87]
	v_or_b32_e32 v84, 22, v130
	v_lshl_add_u64 v[2:3], v[98:99], 0, v[2:3]
	v_ashrrev_i32_e32 v85, 31, v84
	global_load_dword v176, v[2:3], off nt
	v_lshlrev_b64 v[2:3], 17, v[84:85]
	v_or_b32_e32 v82, 23, v130
	v_lshl_add_u64 v[2:3], v[98:99], 0, v[2:3]
	v_ashrrev_i32_e32 v83, 31, v82
	global_load_dword v175, v[2:3], off nt
	v_lshlrev_b64 v[2:3], 17, v[82:83]
	v_or_b32_e32 v80, 24, v130
	v_lshl_add_u64 v[2:3], v[98:99], 0, v[2:3]
	v_ashrrev_i32_e32 v81, 31, v80
	global_load_dword v174, v[2:3], off nt
	v_lshlrev_b64 v[2:3], 17, v[80:81]
	v_or_b32_e32 v78, 25, v130
	v_lshl_add_u64 v[2:3], v[98:99], 0, v[2:3]
	v_ashrrev_i32_e32 v79, 31, v78
	global_load_dword v173, v[2:3], off nt
	v_lshlrev_b64 v[2:3], 17, v[78:79]
	v_or_b32_e32 v76, 26, v130
	v_lshl_add_u64 v[2:3], v[98:99], 0, v[2:3]
	v_ashrrev_i32_e32 v77, 31, v76
	global_load_dword v172, v[2:3], off nt
	v_lshlrev_b64 v[2:3], 17, v[76:77]
	v_or_b32_e32 v74, 27, v130
	v_lshl_add_u64 v[2:3], v[98:99], 0, v[2:3]
	v_ashrrev_i32_e32 v75, 31, v74
	global_load_dword v171, v[2:3], off nt
	v_lshlrev_b64 v[2:3], 17, v[74:75]
	v_or_b32_e32 v72, 28, v130
	v_lshl_add_u64 v[2:3], v[98:99], 0, v[2:3]
	v_ashrrev_i32_e32 v73, 31, v72
	global_load_dword v170, v[2:3], off nt
	v_lshlrev_b64 v[2:3], 17, v[72:73]
	v_or_b32_e32 v70, 29, v130
	v_lshl_add_u64 v[2:3], v[98:99], 0, v[2:3]
	v_ashrrev_i32_e32 v71, 31, v70
	global_load_dword v169, v[2:3], off nt
	v_lshlrev_b64 v[2:3], 17, v[70:71]
	v_or_b32_e32 v68, 30, v130
	v_lshl_add_u64 v[2:3], v[98:99], 0, v[2:3]
	v_ashrrev_i32_e32 v69, 31, v68
	global_load_dword v168, v[2:3], off nt
	v_lshlrev_b64 v[2:3], 17, v[68:69]
	v_or_b32_e32 v66, 31, v130
	v_lshl_add_u64 v[2:3], v[98:99], 0, v[2:3]
	v_ashrrev_i32_e32 v67, 31, v66
	global_load_dword v167, v[2:3], off nt
	v_lshlrev_b64 v[2:3], 17, v[66:67]
	v_or_b32_e32 v64, 32, v130
	v_lshl_add_u64 v[2:3], v[98:99], 0, v[2:3]
	v_ashrrev_i32_e32 v65, 31, v64
	global_load_dword v166, v[2:3], off nt
	v_lshlrev_b64 v[2:3], 17, v[64:65]
	v_or_b32_e32 v62, 33, v130
	v_lshl_add_u64 v[2:3], v[98:99], 0, v[2:3]
	v_ashrrev_i32_e32 v63, 31, v62
	global_load_dword v165, v[2:3], off nt
	v_lshlrev_b64 v[2:3], 17, v[62:63]
	v_or_b32_e32 v60, 34, v130
	v_lshl_add_u64 v[2:3], v[98:99], 0, v[2:3]
	v_ashrrev_i32_e32 v61, 31, v60
	global_load_dword v164, v[2:3], off nt
	v_lshlrev_b64 v[2:3], 17, v[60:61]
	v_or_b32_e32 v58, 35, v130
	v_lshl_add_u64 v[2:3], v[98:99], 0, v[2:3]
	v_ashrrev_i32_e32 v59, 31, v58
	global_load_dword v163, v[2:3], off nt
	v_lshlrev_b64 v[2:3], 17, v[58:59]
	v_or_b32_e32 v56, 36, v130
	v_lshl_add_u64 v[2:3], v[98:99], 0, v[2:3]
	v_ashrrev_i32_e32 v57, 31, v56
	global_load_dword v162, v[2:3], off nt
	v_lshlrev_b64 v[2:3], 17, v[56:57]
	v_or_b32_e32 v54, 37, v130
	v_lshl_add_u64 v[2:3], v[98:99], 0, v[2:3]
	v_ashrrev_i32_e32 v55, 31, v54
	global_load_dword v161, v[2:3], off nt
	v_lshlrev_b64 v[2:3], 17, v[54:55]
	v_or_b32_e32 v52, 38, v130
	v_lshl_add_u64 v[2:3], v[98:99], 0, v[2:3]
	v_ashrrev_i32_e32 v53, 31, v52
	global_load_dword v160, v[2:3], off nt
	v_lshlrev_b64 v[2:3], 17, v[52:53]
	v_or_b32_e32 v50, 39, v130
	v_lshl_add_u64 v[2:3], v[98:99], 0, v[2:3]
	v_ashrrev_i32_e32 v51, 31, v50
	global_load_dword v159, v[2:3], off nt
	v_lshlrev_b64 v[2:3], 17, v[50:51]
	v_or_b32_e32 v48, 40, v130
	v_lshl_add_u64 v[2:3], v[98:99], 0, v[2:3]
	v_ashrrev_i32_e32 v49, 31, v48
	global_load_dword v158, v[2:3], off nt
	v_lshlrev_b64 v[2:3], 17, v[48:49]
	v_or_b32_e32 v46, 41, v130
	v_lshl_add_u64 v[2:3], v[98:99], 0, v[2:3]
	v_ashrrev_i32_e32 v47, 31, v46
	global_load_dword v157, v[2:3], off nt
	v_lshlrev_b64 v[2:3], 17, v[46:47]
	v_or_b32_e32 v44, 42, v130
	v_lshl_add_u64 v[2:3], v[98:99], 0, v[2:3]
	v_ashrrev_i32_e32 v45, 31, v44
	global_load_dword v156, v[2:3], off nt
	v_lshlrev_b64 v[2:3], 17, v[44:45]
	v_or_b32_e32 v42, 43, v130
	v_lshl_add_u64 v[2:3], v[98:99], 0, v[2:3]
	v_ashrrev_i32_e32 v43, 31, v42
	global_load_dword v155, v[2:3], off nt
	v_lshlrev_b64 v[2:3], 17, v[42:43]
	v_or_b32_e32 v40, 44, v130
	v_lshl_add_u64 v[2:3], v[98:99], 0, v[2:3]
	v_ashrrev_i32_e32 v41, 31, v40
	global_load_dword v154, v[2:3], off nt
	v_lshlrev_b64 v[2:3], 17, v[40:41]
	v_or_b32_e32 v38, 45, v130
	v_lshl_add_u64 v[2:3], v[98:99], 0, v[2:3]
	v_ashrrev_i32_e32 v39, 31, v38
	global_load_dword v153, v[2:3], off nt
	v_lshlrev_b64 v[2:3], 17, v[38:39]
	v_or_b32_e32 v36, 46, v130
	v_lshl_add_u64 v[2:3], v[98:99], 0, v[2:3]
	v_ashrrev_i32_e32 v37, 31, v36
	global_load_dword v152, v[2:3], off nt
	v_lshlrev_b64 v[2:3], 17, v[36:37]
	v_or_b32_e32 v34, 47, v130
	v_lshl_add_u64 v[2:3], v[98:99], 0, v[2:3]
	v_ashrrev_i32_e32 v35, 31, v34
	global_load_dword v151, v[2:3], off nt
	v_lshlrev_b64 v[2:3], 17, v[34:35]
	v_or_b32_e32 v32, 48, v130
	v_lshl_add_u64 v[2:3], v[98:99], 0, v[2:3]
	v_ashrrev_i32_e32 v33, 31, v32
	global_load_dword v150, v[2:3], off nt
	v_lshlrev_b64 v[2:3], 17, v[32:33]
	v_or_b32_e32 v30, 49, v130
	v_lshl_add_u64 v[2:3], v[98:99], 0, v[2:3]
	v_ashrrev_i32_e32 v31, 31, v30
	global_load_dword v149, v[2:3], off nt
	v_lshlrev_b64 v[2:3], 17, v[30:31]
	v_or_b32_e32 v28, 50, v130
	v_lshl_add_u64 v[2:3], v[98:99], 0, v[2:3]
	v_ashrrev_i32_e32 v29, 31, v28
	global_load_dword v148, v[2:3], off nt
	v_lshlrev_b64 v[2:3], 17, v[28:29]
	v_or_b32_e32 v26, 51, v130
	v_lshl_add_u64 v[2:3], v[98:99], 0, v[2:3]
	v_ashrrev_i32_e32 v27, 31, v26
	global_load_dword v147, v[2:3], off nt
	v_lshlrev_b64 v[2:3], 17, v[26:27]
	v_or_b32_e32 v24, 52, v130
	v_lshl_add_u64 v[2:3], v[98:99], 0, v[2:3]
	v_ashrrev_i32_e32 v25, 31, v24
	global_load_dword v146, v[2:3], off nt
	v_lshlrev_b64 v[2:3], 17, v[24:25]
	v_or_b32_e32 v22, 53, v130
	v_lshl_add_u64 v[2:3], v[98:99], 0, v[2:3]
	v_ashrrev_i32_e32 v23, 31, v22
	global_load_dword v145, v[2:3], off nt
	v_lshlrev_b64 v[2:3], 17, v[22:23]
	v_or_b32_e32 v20, 54, v130
	v_lshl_add_u64 v[2:3], v[98:99], 0, v[2:3]
	v_ashrrev_i32_e32 v21, 31, v20
	global_load_dword v144, v[2:3], off nt
	v_lshlrev_b64 v[2:3], 17, v[20:21]
	v_or_b32_e32 v18, 55, v130
	v_lshl_add_u64 v[2:3], v[98:99], 0, v[2:3]
	v_ashrrev_i32_e32 v19, 31, v18
	global_load_dword v143, v[2:3], off nt
	v_lshlrev_b64 v[2:3], 17, v[18:19]
	s_waitcnt vmcnt(0)
	v_or_b32_e32 v16, 56, v130
	v_lshl_add_u64 v[2:3], v[98:99], 0, v[2:3]
	v_ashrrev_i32_e32 v17, 31, v16
	global_load_dword v142, v[2:3], off nt
	v_lshlrev_b64 v[2:3], 17, v[16:17]
	v_or_b32_e32 v14, 57, v130
	v_lshl_add_u64 v[2:3], v[98:99], 0, v[2:3]
	v_ashrrev_i32_e32 v15, 31, v14
	global_load_dword v141, v[2:3], off nt
	v_lshlrev_b64 v[2:3], 17, v[14:15]
	v_or_b32_e32 v12, 58, v130
	v_lshl_add_u64 v[2:3], v[98:99], 0, v[2:3]
	v_ashrrev_i32_e32 v13, 31, v12
	global_load_dword v140, v[2:3], off nt
	v_lshlrev_b64 v[2:3], 17, v[12:13]
	v_or_b32_e32 v10, 59, v130
	v_lshl_add_u64 v[2:3], v[98:99], 0, v[2:3]
	v_ashrrev_i32_e32 v11, 31, v10
	global_load_dword v139, v[2:3], off nt
	v_lshlrev_b64 v[2:3], 17, v[10:11]
	v_or_b32_e32 v8, 60, v130
	v_lshl_add_u64 v[2:3], v[98:99], 0, v[2:3]
	v_ashrrev_i32_e32 v9, 31, v8
	global_load_dword v138, v[2:3], off nt
	v_lshlrev_b64 v[2:3], 17, v[8:9]
	v_or_b32_e32 v6, 61, v130
	v_lshl_add_u64 v[2:3], v[98:99], 0, v[2:3]
	v_ashrrev_i32_e32 v7, 31, v6
	global_load_dword v137, v[2:3], off nt
	v_lshlrev_b64 v[2:3], 17, v[6:7]
	v_or_b32_e32 v4, 62, v130
	v_lshl_add_u64 v[2:3], v[98:99], 0, v[2:3]
	v_ashrrev_i32_e32 v5, 31, v4
	global_load_dword v136, v[2:3], off nt
	v_lshlrev_b64 v[2:3], 17, v[4:5]
	v_lshl_add_u64 v[2:3], v[98:99], 0, v[2:3]
	global_load_dword v135, v[2:3], off nt
	v_or_b32_e32 v2, 63, v130
	v_ashrrev_i32_e32 v3, 31, v2
	v_lshlrev_b64 v[192:193], 17, v[2:3]
	v_bfe_u32 v208, v132, 13, 2
	v_lshl_add_u64 v[98:99], v[98:99], 0, v[192:193]
	v_lshl_or_b32 v192, v134, 8, v208
	v_ashrrev_i32_e32 v193, 31, v192
	v_lshl_add_u64 v[192:193], v[192:193], 2, s[76:77]
	global_load_dword v133, v[98:99], off
	global_load_dword v226, v[192:193], off
	v_lshl_or_b32 v192, v128, 2, v208
	v_ashrrev_i32_e32 v193, 31, v192
	v_lshl_add_u64 v[192:193], v[192:193], 2, s[76:77]
	global_load_dword v225, v[192:193], off
	v_lshl_or_b32 v192, v126, 2, v208
	v_ashrrev_i32_e32 v193, 31, v192
	v_lshl_add_u64 v[192:193], v[192:193], 2, s[76:77]
	global_load_dword v224, v[192:193], off
	v_lshl_or_b32 v192, v124, 2, v208
	v_ashrrev_i32_e32 v193, 31, v192
	v_lshl_add_u64 v[192:193], v[192:193], 2, s[76:77]
	global_load_dword v223, v[192:193], off
	v_lshl_or_b32 v192, v122, 2, v208
	v_ashrrev_i32_e32 v193, 31, v192
	v_lshl_add_u64 v[192:193], v[192:193], 2, s[76:77]
	global_load_dword v222, v[192:193], off
	v_lshl_or_b32 v192, v120, 2, v208
	v_ashrrev_i32_e32 v193, 31, v192
	v_lshl_add_u64 v[192:193], v[192:193], 2, s[76:77]
	global_load_dword v221, v[192:193], off
	v_lshl_or_b32 v192, v118, 2, v208
	v_ashrrev_i32_e32 v193, 31, v192
	v_lshl_add_u64 v[192:193], v[192:193], 2, s[76:77]
	global_load_dword v220, v[192:193], off
	v_lshl_or_b32 v192, v116, 2, v208
	v_ashrrev_i32_e32 v193, 31, v192
	v_lshl_add_u64 v[192:193], v[192:193], 2, s[76:77]
	global_load_dword v219, v[192:193], off
	v_lshl_or_b32 v192, v114, 2, v208
	v_ashrrev_i32_e32 v193, 31, v192
	v_lshl_add_u64 v[192:193], v[192:193], 2, s[76:77]
	global_load_dword v218, v[192:193], off
	v_lshl_or_b32 v192, v112, 2, v208
	v_ashrrev_i32_e32 v193, 31, v192
	v_lshl_add_u64 v[192:193], v[192:193], 2, s[76:77]
	global_load_dword v217, v[192:193], off
	v_lshl_or_b32 v192, v110, 2, v208
	v_ashrrev_i32_e32 v193, 31, v192
	v_lshl_add_u64 v[192:193], v[192:193], 2, s[76:77]
	global_load_dword v216, v[192:193], off
	v_lshl_or_b32 v192, v108, 2, v208
	v_ashrrev_i32_e32 v193, 31, v192
	v_lshl_add_u64 v[192:193], v[192:193], 2, s[76:77]
	global_load_dword v215, v[192:193], off
	v_lshl_or_b32 v192, v106, 2, v208
	v_ashrrev_i32_e32 v193, 31, v192
	v_lshl_add_u64 v[192:193], v[192:193], 2, s[76:77]
	global_load_dword v214, v[192:193], off
	v_lshl_or_b32 v192, v104, 2, v208
	v_ashrrev_i32_e32 v193, 31, v192
	v_lshl_add_u64 v[192:193], v[192:193], 2, s[76:77]
	global_load_dword v213, v[192:193], off
	v_lshl_or_b32 v192, v102, 2, v208
	v_ashrrev_i32_e32 v193, 31, v192
	v_lshl_add_u64 v[192:193], v[192:193], 2, s[76:77]
	global_load_dword v212, v[192:193], off
	v_lshlrev_b32_e32 v98, 1, v211
	v_mov_b32_e32 v99, v191
	v_lshl_add_u64 v[98:99], s[24:25], 0, v[98:99]
	v_lshl_or_b32 v192, v100, 2, v208
	v_lshlrev_b64 v[130:131], 16, v[130:131]
	v_lshlrev_b64 v[128:129], 16, v[128:129]
	v_lshlrev_b64 v[126:127], 16, v[126:127]
	v_lshlrev_b64 v[124:125], 16, v[124:125]
	v_lshlrev_b64 v[122:123], 16, v[122:123]
	v_lshlrev_b64 v[120:121], 16, v[120:121]
	v_lshlrev_b64 v[118:119], 16, v[118:119]
	v_lshlrev_b64 v[116:117], 16, v[116:117]
	v_lshlrev_b64 v[114:115], 16, v[114:115]
	v_lshlrev_b64 v[112:113], 16, v[112:113]
	v_lshlrev_b64 v[110:111], 16, v[110:111]
	v_lshlrev_b64 v[108:109], 16, v[108:109]
	v_lshlrev_b64 v[106:107], 16, v[106:107]
	v_lshlrev_b64 v[104:105], 16, v[104:105]
	v_lshlrev_b64 v[102:103], 16, v[102:103]
	v_lshlrev_b64 v[100:101], 16, v[100:101]
	v_lshl_add_u64 v[130:131], v[98:99], 0, v[130:131]
	v_lshl_add_u64 v[128:129], v[98:99], 0, v[128:129]
	v_lshl_add_u64 v[126:127], v[98:99], 0, v[126:127]
	s_waitcnt vmcnt(0)
	v_fmac_f32_e32 v210, 0, v226
	v_lshl_add_u64 v[124:125], v[98:99], 0, v[124:125]
	v_lshl_add_u64 v[122:123], v[98:99], 0, v[122:123]
	v_lshl_add_u64 v[120:121], v[98:99], 0, v[120:121]
	v_fmac_f32_e32 v209, v210, v225
	v_lshl_add_u64 v[118:119], v[98:99], 0, v[118:119]
	v_lshl_add_u64 v[116:117], v[98:99], 0, v[116:117]
	v_lshl_add_u64 v[114:115], v[98:99], 0, v[114:115]
	v_fmac_f32_e32 v207, v209, v224
	v_lshl_add_u64 v[112:113], v[98:99], 0, v[112:113]
	v_lshl_add_u64 v[110:111], v[98:99], 0, v[110:111]
	v_lshl_add_u64 v[108:109], v[98:99], 0, v[108:109]
	v_fmac_f32_e32 v206, v207, v223
	v_lshl_add_u64 v[106:107], v[98:99], 0, v[106:107]
	v_lshl_add_u64 v[104:105], v[98:99], 0, v[104:105]
	v_lshl_add_u64 v[102:103], v[98:99], 0, v[102:103]
	v_fmac_f32_e32 v205, v206, v222
	v_lshl_add_u64 v[100:101], v[98:99], 0, v[100:101]
	v_cvt_pk_bf16_f32 v227, v191, v191
	global_store_short v[130:131], v227, off
	v_fmac_f32_e32 v204, v205, v221
	v_cvt_pk_bf16_f32 v130, v210, v191
	global_store_short v[128:129], v130, off
	v_cvt_pk_bf16_f32 v128, v209, v191
	v_fmac_f32_e32 v203, v204, v220
	global_store_short v[126:127], v128, off
	v_cvt_pk_bf16_f32 v126, v207, v191
	global_store_short v[124:125], v126, off
	v_fmac_f32_e32 v199, v203, v219
	v_cvt_pk_bf16_f32 v124, v206, v191
	global_store_short v[122:123], v124, off
	v_cvt_pk_bf16_f32 v122, v205, v191
	v_fmac_f32_e32 v189, v199, v218
	global_store_short v[120:121], v122, off
	v_cvt_pk_bf16_f32 v120, v204, v191
	global_store_short v[118:119], v120, off
	v_fmac_f32_e32 v188, v189, v217
	v_cvt_pk_bf16_f32 v118, v203, v191
	global_store_short v[116:117], v118, off
	v_cvt_pk_bf16_f32 v116, v199, v191
	v_fmac_f32_e32 v187, v188, v216
	global_store_short v[114:115], v116, off
	v_cvt_pk_bf16_f32 v114, v189, v191
	global_store_short v[112:113], v114, off
	v_fmac_f32_e32 v186, v187, v215
	v_cvt_pk_bf16_f32 v112, v188, v191
	global_store_short v[110:111], v112, off
	v_cvt_pk_bf16_f32 v110, v187, v191
	v_fmac_f32_e32 v185, v186, v214
	global_store_short v[108:109], v110, off
	v_cvt_pk_bf16_f32 v108, v186, v191
	global_store_short v[106:107], v108, off
	v_fmac_f32_e32 v184, v185, v213
	v_cvt_pk_bf16_f32 v106, v185, v191
	global_store_short v[104:105], v106, off
	v_cvt_pk_bf16_f32 v104, v184, v191
	global_store_short v[102:103], v104, off
	v_fmac_f32_e32 v183, v184, v212
	v_cvt_pk_bf16_f32 v102, v183, v191
	global_store_short v[100:101], v102, off
	v_lshl_or_b32 v100, v96, 2, v208
	v_ashrrev_i32_e32 v193, 31, v192
	v_ashrrev_i32_e32 v101, 31, v100
	v_lshl_add_u64 v[192:193], v[192:193], 2, s[76:77]
	v_lshl_add_u64 v[100:101], v[100:101], 2, s[76:77]
	global_load_dword v211, v[192:193], off
	global_load_dword v108, v[100:101], off
	v_lshl_or_b32 v100, v94, 2, v208
	v_ashrrev_i32_e32 v101, 31, v100
	v_lshl_add_u64 v[100:101], v[100:101], 2, s[76:77]
	global_load_dword v109, v[100:101], off
	v_lshl_or_b32 v100, v92, 2, v208
	v_ashrrev_i32_e32 v101, 31, v100
	v_lshl_add_u64 v[100:101], v[100:101], 2, s[76:77]
	global_load_dword v110, v[100:101], off
	v_lshl_or_b32 v100, v90, 2, v208
	v_ashrrev_i32_e32 v101, 31, v100
	v_lshl_add_u64 v[100:101], v[100:101], 2, s[76:77]
	global_load_dword v111, v[100:101], off
	v_lshl_or_b32 v100, v88, 2, v208
	v_ashrrev_i32_e32 v101, 31, v100
	v_lshl_add_u64 v[100:101], v[100:101], 2, s[76:77]
	global_load_dword v112, v[100:101], off
	v_lshl_or_b32 v100, v86, 2, v208
	v_ashrrev_i32_e32 v101, 31, v100
	v_lshl_add_u64 v[100:101], v[100:101], 2, s[76:77]
	global_load_dword v113, v[100:101], off
	v_lshl_or_b32 v100, v84, 2, v208
	v_ashrrev_i32_e32 v101, 31, v100
	v_lshl_add_u64 v[100:101], v[100:101], 2, s[76:77]
	global_load_dword v114, v[100:101], off
	v_lshl_or_b32 v100, v82, 2, v208
	v_ashrrev_i32_e32 v101, 31, v100
	v_lshl_add_u64 v[100:101], v[100:101], 2, s[76:77]
	global_load_dword v115, v[100:101], off
	v_lshl_or_b32 v100, v80, 2, v208
	v_ashrrev_i32_e32 v101, 31, v100
	v_lshl_add_u64 v[100:101], v[100:101], 2, s[76:77]
	global_load_dword v116, v[100:101], off
	v_lshl_or_b32 v100, v78, 2, v208
	v_ashrrev_i32_e32 v101, 31, v100
	v_lshl_add_u64 v[100:101], v[100:101], 2, s[76:77]
	global_load_dword v117, v[100:101], off
	v_lshl_or_b32 v100, v76, 2, v208
	v_ashrrev_i32_e32 v101, 31, v100
	v_lshl_add_u64 v[100:101], v[100:101], 2, s[76:77]
	global_load_dword v105, v[100:101], off
	v_lshl_or_b32 v100, v74, 2, v208
	v_ashrrev_i32_e32 v101, 31, v100
	v_lshl_add_u64 v[100:101], v[100:101], 2, s[76:77]
	global_load_dword v104, v[100:101], off
	v_lshl_or_b32 v100, v72, 2, v208
	v_ashrrev_i32_e32 v101, 31, v100
	v_lshl_add_u64 v[100:101], v[100:101], 2, s[76:77]
	global_load_dword v103, v[100:101], off
	v_lshl_or_b32 v100, v70, 2, v208
	v_ashrrev_i32_e32 v101, 31, v100
	v_lshl_add_u64 v[100:101], v[100:101], 2, s[76:77]
	global_load_dword v102, v[100:101], off
	v_lshl_or_b32 v100, v68, 2, v208
	v_ashrrev_i32_e32 v101, 31, v100
	v_lshl_add_u64 v[100:101], v[100:101], 2, s[76:77]
	global_load_dword v101, v[100:101], off
	v_lshl_or_b32 v106, v66, 2, v208
	v_ashrrev_i32_e32 v107, 31, v106
	v_lshlrev_b64 v[96:97], 16, v[96:97]
	v_lshlrev_b64 v[94:95], 16, v[94:95]
	v_lshlrev_b64 v[92:93], 16, v[92:93]
	v_lshlrev_b64 v[90:91], 16, v[90:91]
	v_lshlrev_b64 v[88:89], 16, v[88:89]
	v_lshlrev_b64 v[86:87], 16, v[86:87]
	v_lshlrev_b64 v[84:85], 16, v[84:85]
	v_lshlrev_b64 v[82:83], 16, v[82:83]
	v_lshlrev_b64 v[80:81], 16, v[80:81]
	v_lshlrev_b64 v[78:79], 16, v[78:79]
	v_lshlrev_b64 v[76:77], 16, v[76:77]
	v_lshlrev_b64 v[74:75], 16, v[74:75]
	v_lshlrev_b64 v[72:73], 16, v[72:73]
	v_lshlrev_b64 v[70:71], 16, v[70:71]
	v_lshlrev_b64 v[68:69], 16, v[68:69]
	v_lshlrev_b64 v[66:67], 16, v[66:67]
	v_lshl_add_u64 v[106:107], v[106:107], 2, s[76:77]
	v_lshl_add_u64 v[96:97], v[98:99], 0, v[96:97]
	v_lshl_add_u64 v[94:95], v[98:99], 0, v[94:95]
	v_lshl_add_u64 v[92:93], v[98:99], 0, v[92:93]
	s_waitcnt vmcnt(0)
	v_fmac_f32_e32 v182, v183, v211
	s_waitcnt vmcnt(14)
	v_fmac_f32_e32 v181, v182, v108
	v_lshl_add_u64 v[90:91], v[98:99], 0, v[90:91]
	v_lshl_add_u64 v[88:89], v[98:99], 0, v[88:89]
	v_lshl_add_u64 v[86:87], v[98:99], 0, v[86:87]
	s_waitcnt vmcnt(13)
	v_fmac_f32_e32 v180, v181, v109
	v_lshl_add_u64 v[84:85], v[98:99], 0, v[84:85]
	v_lshl_add_u64 v[82:83], v[98:99], 0, v[82:83]
	v_lshl_add_u64 v[80:81], v[98:99], 0, v[80:81]
	s_waitcnt vmcnt(12)
	v_fmac_f32_e32 v179, v180, v110
	v_lshl_add_u64 v[78:79], v[98:99], 0, v[78:79]
	v_lshl_add_u64 v[76:77], v[98:99], 0, v[76:77]
	v_lshl_add_u64 v[74:75], v[98:99], 0, v[74:75]
	s_waitcnt vmcnt(11)
	v_fmac_f32_e32 v178, v179, v111
	v_lshl_add_u64 v[72:73], v[98:99], 0, v[72:73]
	v_lshl_add_u64 v[70:71], v[98:99], 0, v[70:71]
	v_lshl_add_u64 v[68:69], v[98:99], 0, v[68:69]
	s_waitcnt vmcnt(10)
	v_fmac_f32_e32 v177, v178, v112
	v_lshl_add_u64 v[66:67], v[98:99], 0, v[66:67]
	global_load_dword v100, v[106:107], off
	v_cvt_pk_bf16_f32 v106, v182, v191
	s_waitcnt vmcnt(10)
	v_fmac_f32_e32 v176, v177, v113
	global_store_short v[96:97], v106, off
	v_cvt_pk_bf16_f32 v96, v181, v191
	global_store_short v[94:95], v96, off
	s_waitcnt vmcnt(11)
	v_fmac_f32_e32 v175, v176, v114
	v_cvt_pk_bf16_f32 v94, v180, v191
	global_store_short v[92:93], v94, off
	v_cvt_pk_bf16_f32 v92, v179, v191
	s_waitcnt vmcnt(11)
	v_fmac_f32_e32 v174, v175, v115
	global_store_short v[90:91], v92, off
	v_cvt_pk_bf16_f32 v90, v178, v191
	global_store_short v[88:89], v90, off
	s_waitcnt vmcnt(12)
	v_fmac_f32_e32 v173, v174, v116
	v_cvt_pk_bf16_f32 v88, v177, v191
	global_store_short v[86:87], v88, off
	v_cvt_pk_bf16_f32 v86, v176, v191
	s_waitcnt vmcnt(12)
	v_fmac_f32_e32 v172, v173, v117
	global_store_short v[84:85], v86, off
	v_cvt_pk_bf16_f32 v84, v175, v191
	global_store_short v[82:83], v84, off
	s_waitcnt vmcnt(13)
	v_fmac_f32_e32 v171, v172, v105
	v_cvt_pk_bf16_f32 v82, v174, v191
	global_store_short v[80:81], v82, off
	v_cvt_pk_bf16_f32 v80, v173, v191
	s_waitcnt vmcnt(13)
	v_fmac_f32_e32 v170, v171, v104
	global_store_short v[78:79], v80, off
	v_cvt_pk_bf16_f32 v78, v172, v191
	global_store_short v[76:77], v78, off
	s_waitcnt vmcnt(14)
	v_fmac_f32_e32 v169, v170, v103
	v_cvt_pk_bf16_f32 v76, v171, v191
	global_store_short v[74:75], v76, off
	v_cvt_pk_bf16_f32 v74, v170, v191
	s_waitcnt vmcnt(14)
	v_fmac_f32_e32 v168, v169, v102
	global_store_short v[72:73], v74, off
	v_cvt_pk_bf16_f32 v72, v169, v191
	global_store_short v[70:71], v72, off
	v_cvt_pk_bf16_f32 v70, v168, v191
	global_store_short v[68:69], v70, off
	s_waitcnt vmcnt(16)
	v_fmac_f32_e32 v167, v168, v101
	v_cvt_pk_bf16_f32 v68, v167, v191
	global_store_short v[66:67], v68, off
	v_lshl_or_b32 v66, v64, 2, v208
	v_ashrrev_i32_e32 v67, 31, v66
	v_lshl_add_u64 v[66:67], v[66:67], 2, s[76:77]
	global_load_dword v74, v[66:67], off
	v_lshl_or_b32 v66, v62, 2, v208
	v_ashrrev_i32_e32 v67, 31, v66
	v_lshl_add_u64 v[66:67], v[66:67], 2, s[76:77]
	global_load_dword v75, v[66:67], off
	v_lshl_or_b32 v66, v60, 2, v208
	v_ashrrev_i32_e32 v67, 31, v66
	v_lshl_add_u64 v[66:67], v[66:67], 2, s[76:77]
	global_load_dword v76, v[66:67], off
	v_lshl_or_b32 v66, v58, 2, v208
	v_ashrrev_i32_e32 v67, 31, v66
	v_lshl_add_u64 v[66:67], v[66:67], 2, s[76:77]
	global_load_dword v77, v[66:67], off
	v_lshl_or_b32 v66, v56, 2, v208
	v_ashrrev_i32_e32 v67, 31, v66
	v_lshl_add_u64 v[66:67], v[66:67], 2, s[76:77]
	global_load_dword v78, v[66:67], off
	v_lshl_or_b32 v66, v54, 2, v208
	v_ashrrev_i32_e32 v67, 31, v66
	v_lshl_add_u64 v[66:67], v[66:67], 2, s[76:77]
	global_load_dword v79, v[66:67], off
	v_lshl_or_b32 v66, v52, 2, v208
	v_ashrrev_i32_e32 v67, 31, v66
	v_lshl_add_u64 v[66:67], v[66:67], 2, s[76:77]
	global_load_dword v80, v[66:67], off
	v_lshl_or_b32 v66, v50, 2, v208
	v_ashrrev_i32_e32 v67, 31, v66
	v_lshl_add_u64 v[66:67], v[66:67], 2, s[76:77]
	global_load_dword v81, v[66:67], off
	v_lshl_or_b32 v66, v48, 2, v208
	v_ashrrev_i32_e32 v67, 31, v66
	v_lshl_add_u64 v[66:67], v[66:67], 2, s[76:77]
	global_load_dword v82, v[66:67], off
	v_lshl_or_b32 v66, v46, 2, v208
	v_ashrrev_i32_e32 v67, 31, v66
	v_lshl_add_u64 v[66:67], v[66:67], 2, s[76:77]
	global_load_dword v83, v[66:67], off
	v_lshl_or_b32 v66, v44, 2, v208
	v_ashrrev_i32_e32 v67, 31, v66
	v_lshl_add_u64 v[66:67], v[66:67], 2, s[76:77]
	global_load_dword v71, v[66:67], off
	v_lshl_or_b32 v66, v42, 2, v208
	v_ashrrev_i32_e32 v67, 31, v66
	v_lshl_add_u64 v[66:67], v[66:67], 2, s[76:77]
	global_load_dword v70, v[66:67], off
	v_lshl_or_b32 v66, v40, 2, v208
	v_ashrrev_i32_e32 v67, 31, v66
	v_lshl_add_u64 v[66:67], v[66:67], 2, s[76:77]
	global_load_dword v69, v[66:67], off
	v_lshl_or_b32 v66, v38, 2, v208
	v_ashrrev_i32_e32 v67, 31, v66
	v_lshl_add_u64 v[66:67], v[66:67], 2, s[76:77]
	global_load_dword v68, v[66:67], off
	v_lshl_or_b32 v66, v36, 2, v208
	v_ashrrev_i32_e32 v67, 31, v66
	v_lshl_add_u64 v[66:67], v[66:67], 2, s[76:77]
	global_load_dword v67, v[66:67], off
	s_waitcnt vmcnt(0)
	v_fmac_f32_e32 v166, v167, v100
	v_lshl_or_b32 v72, v34, 2, v208
	v_ashrrev_i32_e32 v73, 31, v72
	v_lshlrev_b64 v[64:65], 16, v[64:65]
	v_lshlrev_b64 v[62:63], 16, v[62:63]
	v_lshlrev_b64 v[60:61], 16, v[60:61]
	v_lshlrev_b64 v[58:59], 16, v[58:59]
	v_lshlrev_b64 v[56:57], 16, v[56:57]
	v_lshlrev_b64 v[54:55], 16, v[54:55]
	v_lshlrev_b64 v[52:53], 16, v[52:53]
	v_lshlrev_b64 v[50:51], 16, v[50:51]
	v_lshlrev_b64 v[48:49], 16, v[48:49]
	v_lshlrev_b64 v[46:47], 16, v[46:47]
	v_lshlrev_b64 v[44:45], 16, v[44:45]
	v_lshlrev_b64 v[42:43], 16, v[42:43]
	v_lshlrev_b64 v[40:41], 16, v[40:41]
	v_lshlrev_b64 v[38:39], 16, v[38:39]
	v_lshlrev_b64 v[36:37], 16, v[36:37]
	v_lshlrev_b64 v[34:35], 16, v[34:35]
	v_lshl_add_u64 v[72:73], v[72:73], 2, s[76:77]
	v_lshl_add_u64 v[64:65], v[98:99], 0, v[64:65]
	v_lshl_add_u64 v[62:63], v[98:99], 0, v[62:63]
	v_lshl_add_u64 v[60:61], v[98:99], 0, v[60:61]
	s_waitcnt vmcnt(14)
	v_fmac_f32_e32 v165, v166, v74
	v_lshl_add_u64 v[58:59], v[98:99], 0, v[58:59]
	v_lshl_add_u64 v[56:57], v[98:99], 0, v[56:57]
	v_lshl_add_u64 v[54:55], v[98:99], 0, v[54:55]
	s_waitcnt vmcnt(13)
	v_fmac_f32_e32 v164, v165, v75
	v_lshl_add_u64 v[52:53], v[98:99], 0, v[52:53]
	v_lshl_add_u64 v[50:51], v[98:99], 0, v[50:51]
	v_lshl_add_u64 v[48:49], v[98:99], 0, v[48:49]
	s_waitcnt vmcnt(12)
	v_fmac_f32_e32 v163, v164, v76
	v_lshl_add_u64 v[46:47], v[98:99], 0, v[46:47]
	v_lshl_add_u64 v[44:45], v[98:99], 0, v[44:45]
	v_lshl_add_u64 v[42:43], v[98:99], 0, v[42:43]
	s_waitcnt vmcnt(11)
	v_fmac_f32_e32 v162, v163, v77
	v_lshl_add_u64 v[40:41], v[98:99], 0, v[40:41]
	v_lshl_add_u64 v[38:39], v[98:99], 0, v[38:39]
	v_lshl_add_u64 v[36:37], v[98:99], 0, v[36:37]
	s_waitcnt vmcnt(10)
	v_fmac_f32_e32 v161, v162, v78
	v_lshl_add_u64 v[34:35], v[98:99], 0, v[34:35]
	global_load_dword v66, v[72:73], off
	v_cvt_pk_bf16_f32 v72, v166, v191
	s_waitcnt vmcnt(10)
	v_fmac_f32_e32 v160, v161, v79
	global_store_short v[64:65], v72, off
	v_cvt_pk_bf16_f32 v64, v165, v191
	global_store_short v[62:63], v64, off
	s_waitcnt vmcnt(11)
	v_fmac_f32_e32 v159, v160, v80
	v_cvt_pk_bf16_f32 v62, v164, v191
	global_store_short v[60:61], v62, off
	v_cvt_pk_bf16_f32 v60, v163, v191
	s_waitcnt vmcnt(11)
	v_fmac_f32_e32 v158, v159, v81
	global_store_short v[58:59], v60, off
	v_cvt_pk_bf16_f32 v58, v162, v191
	global_store_short v[56:57], v58, off
	s_waitcnt vmcnt(12)
	v_fmac_f32_e32 v157, v158, v82
	v_cvt_pk_bf16_f32 v56, v161, v191
	global_store_short v[54:55], v56, off
	v_cvt_pk_bf16_f32 v54, v160, v191
	s_waitcnt vmcnt(12)
	v_fmac_f32_e32 v156, v157, v83
	global_store_short v[52:53], v54, off
	v_cvt_pk_bf16_f32 v52, v159, v191
	global_store_short v[50:51], v52, off
	s_waitcnt vmcnt(13)
	v_fmac_f32_e32 v155, v156, v71
	v_cvt_pk_bf16_f32 v50, v158, v191
	global_store_short v[48:49], v50, off
	v_cvt_pk_bf16_f32 v48, v157, v191
	s_waitcnt vmcnt(13)
	v_fmac_f32_e32 v154, v155, v70
	global_store_short v[46:47], v48, off
	v_cvt_pk_bf16_f32 v46, v156, v191
	global_store_short v[44:45], v46, off
	s_waitcnt vmcnt(14)
	v_fmac_f32_e32 v153, v154, v69
	v_cvt_pk_bf16_f32 v44, v155, v191
	global_store_short v[42:43], v44, off
	v_cvt_pk_bf16_f32 v42, v154, v191
	s_waitcnt vmcnt(14)
	v_fmac_f32_e32 v152, v153, v68
	global_store_short v[40:41], v42, off
	v_cvt_pk_bf16_f32 v40, v153, v191
	global_store_short v[38:39], v40, off
	v_cvt_pk_bf16_f32 v38, v152, v191
	global_store_short v[36:37], v38, off
	s_waitcnt vmcnt(16)
	v_fmac_f32_e32 v151, v152, v67
	v_cvt_pk_bf16_f32 v36, v151, v191
	global_store_short v[34:35], v36, off
	v_lshl_or_b32 v34, v32, 2, v208
	v_ashrrev_i32_e32 v35, 31, v34
	v_lshl_add_u64 v[34:35], v[34:35], 2, s[76:77]
	global_load_dword v42, v[34:35], off
	v_lshl_or_b32 v34, v30, 2, v208
	v_ashrrev_i32_e32 v35, 31, v34
	v_lshl_add_u64 v[34:35], v[34:35], 2, s[76:77]
	global_load_dword v43, v[34:35], off
	v_lshl_or_b32 v34, v28, 2, v208
	v_ashrrev_i32_e32 v35, 31, v34
	v_lshl_add_u64 v[34:35], v[34:35], 2, s[76:77]
	global_load_dword v44, v[34:35], off
	v_lshl_or_b32 v34, v26, 2, v208
	v_ashrrev_i32_e32 v35, 31, v34
	v_lshl_add_u64 v[34:35], v[34:35], 2, s[76:77]
	global_load_dword v45, v[34:35], off
	v_lshl_or_b32 v34, v24, 2, v208
	v_ashrrev_i32_e32 v35, 31, v34
	v_lshl_add_u64 v[34:35], v[34:35], 2, s[76:77]
	global_load_dword v46, v[34:35], off
	v_lshl_or_b32 v34, v22, 2, v208
	v_ashrrev_i32_e32 v35, 31, v34
	v_lshl_add_u64 v[34:35], v[34:35], 2, s[76:77]
	global_load_dword v47, v[34:35], off
	v_lshl_or_b32 v34, v20, 2, v208
	v_ashrrev_i32_e32 v35, 31, v34
	v_lshl_add_u64 v[34:35], v[34:35], 2, s[76:77]
	global_load_dword v48, v[34:35], off
	v_lshl_or_b32 v34, v18, 2, v208
	v_ashrrev_i32_e32 v35, 31, v34
	v_lshl_add_u64 v[34:35], v[34:35], 2, s[76:77]
	global_load_dword v49, v[34:35], off
	v_lshl_or_b32 v34, v16, 2, v208
	v_ashrrev_i32_e32 v35, 31, v34
	v_lshl_add_u64 v[34:35], v[34:35], 2, s[76:77]
	global_load_dword v50, v[34:35], off
	v_lshl_or_b32 v34, v14, 2, v208
	v_ashrrev_i32_e32 v35, 31, v34
	v_lshl_add_u64 v[34:35], v[34:35], 2, s[76:77]
	global_load_dword v51, v[34:35], off
	v_lshl_or_b32 v34, v12, 2, v208
	v_ashrrev_i32_e32 v35, 31, v34
	v_lshl_add_u64 v[34:35], v[34:35], 2, s[76:77]
	global_load_dword v39, v[34:35], off
	v_lshl_or_b32 v34, v10, 2, v208
	v_ashrrev_i32_e32 v35, 31, v34
	v_lshl_add_u64 v[34:35], v[34:35], 2, s[76:77]
	global_load_dword v38, v[34:35], off
	v_lshl_or_b32 v34, v8, 2, v208
	v_ashrrev_i32_e32 v35, 31, v34
	v_lshl_add_u64 v[34:35], v[34:35], 2, s[76:77]
	global_load_dword v37, v[34:35], off
	v_lshl_or_b32 v34, v6, 2, v208
	v_ashrrev_i32_e32 v35, 31, v34
	v_lshl_add_u64 v[34:35], v[34:35], 2, s[76:77]
	global_load_dword v36, v[34:35], off
	v_lshl_or_b32 v34, v4, 2, v208
	v_ashrrev_i32_e32 v35, 31, v34
	v_lshl_add_u64 v[34:35], v[34:35], 2, s[76:77]
	global_load_dword v35, v[34:35], off
	v_lshl_or_b32 v40, v2, 2, v208
	v_ashrrev_i32_e32 v41, 31, v40
	v_lshl_add_u64 v[40:41], v[40:41], 2, s[76:77]
	global_load_dword v34, v[40:41], off
	s_waitcnt vmcnt(0)
	v_fmac_f32_e32 v150, v151, v66
	v_lshlrev_b64 v[32:33], 16, v[32:33]
	v_lshlrev_b64 v[30:31], 16, v[30:31]
	v_lshlrev_b64 v[28:29], 16, v[28:29]
	v_lshlrev_b64 v[26:27], 16, v[26:27]
	v_lshlrev_b64 v[24:25], 16, v[24:25]
	v_lshlrev_b64 v[22:23], 16, v[22:23]
	v_lshlrev_b64 v[20:21], 16, v[20:21]
	v_lshlrev_b64 v[18:19], 16, v[18:19]
	v_lshlrev_b64 v[16:17], 16, v[16:17]
	v_lshlrev_b64 v[14:15], 16, v[14:15]
	v_lshlrev_b64 v[12:13], 16, v[12:13]
	v_lshlrev_b64 v[10:11], 16, v[10:11]
	v_lshlrev_b64 v[8:9], 16, v[8:9]
	v_lshlrev_b64 v[6:7], 16, v[6:7]
	v_lshlrev_b64 v[4:5], 16, v[4:5]
	v_lshlrev_b64 v[2:3], 16, v[2:3]
	v_lshl_add_u64 v[32:33], v[98:99], 0, v[32:33]
	v_lshl_add_u64 v[30:31], v[98:99], 0, v[30:31]
	s_waitcnt vmcnt(15)
	v_fmac_f32_e32 v149, v150, v42
	v_lshl_add_u64 v[28:29], v[98:99], 0, v[28:29]
	v_lshl_add_u64 v[26:27], v[98:99], 0, v[26:27]
	v_lshl_add_u64 v[24:25], v[98:99], 0, v[24:25]
	s_waitcnt vmcnt(14)
	v_fmac_f32_e32 v148, v149, v43
	v_lshl_add_u64 v[22:23], v[98:99], 0, v[22:23]
	v_lshl_add_u64 v[20:21], v[98:99], 0, v[20:21]
	v_lshl_add_u64 v[18:19], v[98:99], 0, v[18:19]
	s_waitcnt vmcnt(13)
	v_fmac_f32_e32 v147, v148, v44
	v_lshl_add_u64 v[16:17], v[98:99], 0, v[16:17]
	v_lshl_add_u64 v[14:15], v[98:99], 0, v[14:15]
	v_lshl_add_u64 v[12:13], v[98:99], 0, v[12:13]
	s_waitcnt vmcnt(12)
	v_fmac_f32_e32 v146, v147, v45
	v_lshl_add_u64 v[10:11], v[98:99], 0, v[10:11]
	v_lshl_add_u64 v[8:9], v[98:99], 0, v[8:9]
	v_lshl_add_u64 v[6:7], v[98:99], 0, v[6:7]
	s_waitcnt vmcnt(11)
	v_fmac_f32_e32 v145, v146, v46
	v_lshl_add_u64 v[4:5], v[98:99], 0, v[4:5]
	v_lshl_add_u64 v[2:3], v[98:99], 0, v[2:3]
	v_cvt_pk_bf16_f32 v40, v150, v191
	s_waitcnt vmcnt(10)
	v_fmac_f32_e32 v144, v145, v47
	global_store_short v[32:33], v40, off
	v_cvt_pk_bf16_f32 v32, v149, v191
	global_store_short v[30:31], v32, off
	s_waitcnt vmcnt(11)
	v_fmac_f32_e32 v143, v144, v48
	v_cvt_pk_bf16_f32 v30, v148, v191
	global_store_short v[28:29], v30, off
	v_cvt_pk_bf16_f32 v28, v147, v191
	s_waitcnt vmcnt(11)
	v_fmac_f32_e32 v142, v143, v49
	global_store_short v[26:27], v28, off
	v_cvt_pk_bf16_f32 v26, v146, v191
	global_store_short v[24:25], v26, off
	s_waitcnt vmcnt(12)
	v_fmac_f32_e32 v141, v142, v50
	v_cvt_pk_bf16_f32 v24, v145, v191
	global_store_short v[22:23], v24, off
	v_cvt_pk_bf16_f32 v22, v144, v191
	s_waitcnt vmcnt(12)
	v_fmac_f32_e32 v140, v141, v51
	global_store_short v[20:21], v22, off
	v_cvt_pk_bf16_f32 v20, v143, v191
	global_store_short v[18:19], v20, off
	s_waitcnt vmcnt(13)
	v_fmac_f32_e32 v139, v140, v39
	v_cvt_pk_bf16_f32 v18, v142, v191
	global_store_short v[16:17], v18, off
	v_cvt_pk_bf16_f32 v16, v141, v191
	s_waitcnt vmcnt(13)
	v_fmac_f32_e32 v138, v139, v38
	global_store_short v[14:15], v16, off
	v_cvt_pk_bf16_f32 v14, v140, v191
	global_store_short v[12:13], v14, off
	s_waitcnt vmcnt(14)
	v_fmac_f32_e32 v137, v138, v37
	v_cvt_pk_bf16_f32 v12, v139, v191
	global_store_short v[10:11], v12, off
	v_cvt_pk_bf16_f32 v10, v138, v191
	s_waitcnt vmcnt(14)
	v_fmac_f32_e32 v136, v137, v36
	global_store_short v[8:9], v10, off
	v_cvt_pk_bf16_f32 v8, v137, v191
	global_store_short v[6:7], v8, off
	v_cvt_pk_bf16_f32 v6, v136, v191
	global_store_short v[4:5], v6, off
	s_waitcnt vmcnt(16)
	v_fmac_f32_e32 v135, v136, v35
	v_cvt_pk_bf16_f32 v4, v135, v191
	global_store_short v[2:3], v4, off
	v_add_u32_e32 v2, s4, v134
	v_ashrrev_i32_e32 v3, 31, v2
	v_lshlrev_b64 v[2:3], 17, v[2:3]
	v_lshl_add_u64 v[2:3], s[20:21], 0, v[2:3]
	v_lshl_add_u64 v[2:3], v[2:3], 0, v[190:191]
	v_add_co_u32_e32 v2, vcc, 0x4200000, v2
	s_waitcnt vmcnt(16)
	v_fmac_f32_e32 v133, v135, v34
	v_addc_co_u32_e32 v3, vcc, 0, v3, vcc
	global_store_dword v[2:3], v133, off
	s_load_dword s5, s[66:67], 0x0
	s_waitcnt lgkmcnt(0)
	v_lshl_add_u32 v132, s5, 9, v132
	s_mov_b32 s5, 0x1ffff
	v_cmp_lt_i32_e32 vcc, s5, v132
	s_or_b64 s[2:3], vcc, s[2:3]
	s_andn2_b64 exec, exec, s[2:3]
	s_cbranch_execnz .LBB0_439

.LBB0_1215:
	v_add_u32_e32 v42, s13, v44
	v_ashrrev_i32_e32 v43, 31, v42
	v_mul_lo_u32 v6, s0, v43
	v_mul_lo_u32 v7, s1, v42
	v_mad_u64_u32 v[2:3], s[6:7], s0, v42, 0
	v_add3_u32 v3, v3, v6, v7
	v_add_u32_e32 v6, 32, v42
	v_ashrrev_i32_e32 v7, 31, v6
	v_mul_lo_u32 v8, s0, v7
	v_mul_lo_u32 v9, s1, v6
	v_mad_u64_u32 v[6:7], s[6:7], s0, v6, 0
	v_lshl_add_u64 v[2:3], v[2:3], 2, v[4:5]
	v_add3_u32 v7, v7, v8, v9
	v_lshl_add_u64 v[6:7], v[6:7], 2, v[4:5]
	global_load_dwordx4 v[30:33], v[2:3], off nt
	global_load_dwordx4 v[22:25], v[6:7], off nt
	v_add_u32_e32 v2, 64, v42
	v_ashrrev_i32_e32 v3, 31, v2
	v_mul_lo_u32 v6, s0, v3
	v_mul_lo_u32 v7, s1, v2
	v_mad_u64_u32 v[2:3], s[6:7], s0, v2, 0
	v_add3_u32 v3, v3, v6, v7
	v_add_u32_e32 v6, 0x60, v42
	v_ashrrev_i32_e32 v7, 31, v6
	v_mul_lo_u32 v8, s0, v7
	v_mul_lo_u32 v9, s1, v6
	v_mad_u64_u32 v[6:7], s[6:7], s0, v6, 0
	v_lshl_add_u64 v[2:3], v[2:3], 2, v[4:5]
	v_add3_u32 v7, v7, v8, v9
	v_lshl_add_u64 v[6:7], v[6:7], 2, v[4:5]
	global_load_dwordx4 v[26:29], v[2:3], off nt
	global_load_dwordx4 v[14:17], v[6:7], off nt
	v_add_u32_e32 v2, 0x80, v42
	v_ashrrev_i32_e32 v3, 31, v2
	v_mul_lo_u32 v6, s0, v3
	v_mul_lo_u32 v7, s1, v2
	v_mad_u64_u32 v[2:3], s[6:7], s0, v2, 0
	v_add3_u32 v3, v3, v6, v7
	v_add_u32_e32 v6, 0xa0, v42
	v_ashrrev_i32_e32 v7, 31, v6
	v_mul_lo_u32 v8, s0, v7
	v_mul_lo_u32 v9, s1, v6
	v_mad_u64_u32 v[6:7], s[6:7], s0, v6, 0
	v_add3_u32 v7, v7, v8, v9
	v_lshl_add_u64 v[2:3], v[2:3], 2, v[4:5]
	v_lshl_add_u64 v[6:7], v[6:7], 2, v[4:5]
	global_load_dwordx4 v[18:21], v[2:3], off nt
	s_nop 0
	global_load_dwordx4 v[6:9], v[6:7], off nt
	v_add_u32_e32 v2, 0xc0, v42
	v_ashrrev_i32_e32 v3, 31, v2
	v_mul_lo_u32 v10, s0, v3
	v_mul_lo_u32 v11, s1, v2
	v_mad_u64_u32 v[2:3], s[6:7], s0, v2, 0
	v_add3_u32 v3, v3, v10, v11
	v_add_u32_e32 v10, 0xe0, v42
	v_ashrrev_i32_e32 v11, 31, v10
	v_mul_lo_u32 v12, s0, v11
	v_mul_lo_u32 v13, s1, v10
	v_mad_u64_u32 v[10:11], s[0:1], s0, v10, 0
	v_add3_u32 v11, v11, v12, v13
	v_lshl_add_u64 v[2:3], v[2:3], 2, v[4:5]
	v_lshl_add_u64 v[4:5], v[10:11], 2, v[4:5]
	global_load_dwordx4 v[10:13], v[2:3], off nt
	s_nop 0
	global_load_dwordx4 v[2:5], v[4:5], off nt
	s_cmp_lt_i32 s12, 2
	s_mov_b64 s[6:7], -1
	s_waitcnt vmcnt(0) lgkmcnt(0)
	s_barrier
	s_cbranch_scc1 .LBB0_1218
	s_mov_b64 s[6:7], 0
	s_cmp_eq_u32 s12, 2
	s_mov_b64 s[0:1], 0
	s_cbranch_scc0 .LBB0_1218
	s_lshl_b32 s0, s2, 10
	s_ashr_i32 s1, s0, 31
	s_mov_b64 s[14:15], s[74:75]
	v_readlane_b32 s60, v252, 5
	s_lshl_b64 s[0:1], s[0:1], 2
	v_readlane_b32 s72, v252, 17
	v_readlane_b32 s73, v252, 18
	v_readlane_b32 s74, v252, 19
	v_readlane_b32 s68, v252, 13
	v_readlane_b32 s69, v252, 14
	v_readlane_b32 s70, v252, 15
	v_readlane_b32 s71, v252, 16
	v_readlane_b32 s75, v252, 20
	v_readlane_b32 s72, v252, 44
	s_add_u32 s0, s74, s0
	v_readlane_b32 s73, v252, 45
	s_mov_b64 s[70:71], s[42:43]
	s_mov_b64 s[68:69], s[40:41]
	s_addc_u32 s1, s75, s1
	s_mov_b64 s[74:75], s[14:15]
	v_readlane_b32 s61, v252, 6
	v_readlane_b32 s62, v252, 7
	v_readlane_b32 s63, v252, 8
	v_readlane_b32 s64, v252, 9
	v_readlane_b32 s65, v252, 10
	v_readlane_b32 s66, v252, 11
	v_readlane_b32 s67, v252, 12

.LBB0_1296:
	v_add_u32_e32 v40, s11, v43
	v_ashrrev_i32_e32 v41, 31, v40
	s_waitcnt vmcnt(0)
	v_mul_lo_u32 v6, s0, v41
	v_mul_lo_u32 v7, s1, v40
	v_mad_u64_u32 v[2:3], s[6:7], s0, v40, 0
	v_add3_u32 v3, v3, v6, v7
	v_add_u32_e32 v6, 32, v40
	v_ashrrev_i32_e32 v7, 31, v6
	v_mul_lo_u32 v8, s0, v7
	v_mul_lo_u32 v9, s1, v6
	v_mad_u64_u32 v[6:7], s[6:7], s0, v6, 0
	v_lshl_add_u64 v[2:3], v[2:3], 2, v[4:5]
	v_add3_u32 v7, v7, v8, v9
	v_lshl_add_u64 v[6:7], v[6:7], 2, v[4:5]
	global_load_dwordx4 v[30:33], v[2:3], off nt
	global_load_dwordx4 v[22:25], v[6:7], off nt
	v_add_u32_e32 v2, 64, v40
	v_ashrrev_i32_e32 v3, 31, v2
	v_mul_lo_u32 v6, s0, v3
	v_mul_lo_u32 v7, s1, v2
	v_mad_u64_u32 v[2:3], s[6:7], s0, v2, 0
	v_add3_u32 v3, v3, v6, v7
	v_add_u32_e32 v6, 0x60, v40
	v_ashrrev_i32_e32 v7, 31, v6
	v_mul_lo_u32 v8, s0, v7
	v_mul_lo_u32 v9, s1, v6
	v_mad_u64_u32 v[6:7], s[6:7], s0, v6, 0
	v_lshl_add_u64 v[2:3], v[2:3], 2, v[4:5]
	v_add3_u32 v7, v7, v8, v9
	v_lshl_add_u64 v[6:7], v[6:7], 2, v[4:5]
	global_load_dwordx4 v[26:29], v[2:3], off nt
	global_load_dwordx4 v[14:17], v[6:7], off nt
	v_add_u32_e32 v2, 0x80, v40
	v_ashrrev_i32_e32 v3, 31, v2
	v_mul_lo_u32 v6, s0, v3
	v_mul_lo_u32 v7, s1, v2
	v_mad_u64_u32 v[2:3], s[6:7], s0, v2, 0
	v_add3_u32 v3, v3, v6, v7
	v_add_u32_e32 v6, 0xa0, v40
	v_ashrrev_i32_e32 v7, 31, v6
	v_mul_lo_u32 v8, s0, v7
	v_mul_lo_u32 v9, s1, v6
	v_mad_u64_u32 v[6:7], s[6:7], s0, v6, 0
	v_add3_u32 v7, v7, v8, v9
	v_lshl_add_u64 v[2:3], v[2:3], 2, v[4:5]
	v_lshl_add_u64 v[6:7], v[6:7], 2, v[4:5]
	global_load_dwordx4 v[18:21], v[2:3], off nt
	s_nop 0
	global_load_dwordx4 v[6:9], v[6:7], off nt
	v_add_u32_e32 v2, 0xc0, v40
	v_ashrrev_i32_e32 v3, 31, v2
	v_mul_lo_u32 v10, s0, v3
	v_mul_lo_u32 v11, s1, v2
	v_mad_u64_u32 v[2:3], s[6:7], s0, v2, 0
	v_add3_u32 v3, v3, v10, v11
	v_add_u32_e32 v10, 0xe0, v40
	v_ashrrev_i32_e32 v11, 31, v10
	v_mul_lo_u32 v12, s0, v11
	v_mul_lo_u32 v13, s1, v10
	v_mad_u64_u32 v[10:11], s[0:1], s0, v10, 0
	v_add3_u32 v11, v11, v12, v13
	v_lshl_add_u64 v[2:3], v[2:3], 2, v[4:5]
	v_lshl_add_u64 v[4:5], v[10:11], 2, v[4:5]
	global_load_dwordx4 v[10:13], v[2:3], off nt
	s_nop 0
	global_load_dwordx4 v[2:5], v[4:5], off nt
	s_cmp_lt_i32 s10, 2
	s_mov_b64 s[6:7], -1
	s_waitcnt vmcnt(0) lgkmcnt(0)
	s_barrier
	s_cbranch_scc1 .LBB0_1299
	s_mov_b64 s[6:7], 0
	s_cmp_eq_u32 s10, 2
	s_mov_b64 s[0:1], 0
	s_cbranch_scc0 .LBB0_1299
	s_lshl_b32 s0, s2, 10
	s_ashr_i32 s1, s0, 31
	v_readlane_b32 s60, v252, 5
	s_lshl_b64 s[0:1], s[0:1], 2
	v_readlane_b32 s72, v252, 17
	v_readlane_b32 s73, v252, 18
	v_readlane_b32 s74, v252, 19
	v_readlane_b32 s75, v252, 20
	v_readlane_b32 s72, v252, 44
	s_add_u32 s0, s74, s0
	v_readlane_b32 s73, v252, 45
	s_mov_b64 s[40:41], s[50:51]
	s_addc_u32 s1, s75, s1
	v_readlane_b32 s61, v252, 6
	v_readlane_b32 s62, v252, 7
	v_readlane_b32 s63, v252, 8
	v_readlane_b32 s64, v252, 9
	v_readlane_b32 s65, v252, 10
	v_readlane_b32 s66, v252, 11
	v_readlane_b32 s67, v252, 12
	v_readlane_b32 s68, v252, 13
	v_readlane_b32 s69, v252, 14
	v_readlane_b32 s70, v252, 15
	v_readlane_b32 s71, v252, 16

.LBB0_1339:
	v_ashrrev_i32_e32 v28, 6, v202
	s_add_i32 s9, s8, 0xffffff5f
	s_mov_b64 s[4:5], s[72:73]
	v_readlane_b32 s60, v251, 53
	v_lshl_add_u32 v4, s9, 3, v28
	v_readlane_b32 s61, v251, 54
	v_readlane_b32 s63, v251, 56
	v_readlane_b32 s62, v251, 55
	v_mov_b32_e32 v3, s61
	v_mov_b32_e32 v2, s63
	v_cmp_gt_i32_e32 vcc, s35, v4
	v_mov_b32_e32 v5, s60
	v_add_u32_e32 v6, 0xffffc000, v4
	v_cndmask_b32_e32 v3, v2, v3, vcc
	v_mov_b32_e32 v2, s62
	v_cndmask_b32_e32 v2, v2, v5, vcc
	v_ashrrev_i32_e32 v5, 31, v4
	v_cndmask_b32_e32 v5, 0, v5, vcc
	v_cndmask_b32_e32 v4, v6, v4, vcc
	v_and_b32_e32 v18, 0xfc, v37
	v_lshlrev_b64 v[4:5], 12, v[4:5]
	v_lshl_add_u64 v[2:3], v[2:3], 0, v[4:5]
	v_lshlrev_b32_e32 v190, 2, v18
	v_lshl_add_u64 v[2:3], v[2:3], 0, v[190:191]
	global_load_dwordx4 v[6:9], v[2:3], off offset:3072 nt
	global_load_dwordx4 v[10:13], v[2:3], off offset:2048 nt
	global_load_dwordx4 v[14:17], v[2:3], off offset:1024 nt
	s_nop 0
	global_load_dwordx4 v[2:5], v[2:3], off nt
	s_load_dword s10, s[50:51], 0x0
	v_and_b32_e32 v19, 63, v202
	v_lshlrev_b32_e32 v20, 3, v19
	v_mov_b32_e32 v21, v191
	v_lshlrev_b32_e32 v190, 2, v19
	v_lshl_add_u64 v[20:21], s[4:5], 0, v[20:21]
	s_mov_b64 s[0:1], 0x2f08000
	v_lshl_add_u64 v[22:23], v[20:21], 0, s[0:1]
	v_cmp_gt_u32_e64 s[0:1], 16, v19
	v_cmp_eq_u32_e64 s[2:3], 0, v19
	v_lshl_add_u64 v[20:21], s[4:5], 0, v[190:191]
	s_mov_b64 s[4:5], 0x5008000
	v_lshl_add_u32 v19, s8, 3, v28
	v_lshl_add_u64 v[24:25], v[20:21], 0, s[4:5]
	v_add_u32_e32 v26, 0xfffffaf8, v19
	s_waitcnt lgkmcnt(0)
	s_lshl_b32 s8, s10, 3
	v_lshlrev_b32_e32 v190, 2, v18
	v_readlane_b32 s64, v251, 57
	v_readlane_b32 s65, v251, 58
	v_readlane_b32 s66, v251, 59
	v_readlane_b32 s67, v251, 60
	v_readlane_b32 s68, v251, 61
	v_readlane_b32 s69, v251, 62
	v_readlane_b32 s70, v251, 63
	v_readlane_b32 s71, v252, 0
	v_readlane_b32 s72, v252, 1
	v_readlane_b32 s73, v252, 2
	v_readlane_b32 s74, v252, 3
	v_readlane_b32 s75, v252, 4
	s_branch .LBB0_1341

.LBB0_1341:
	s_mov_b32 s6, s9
	s_add_i32 s9, s10, s9
	s_cmpk_gt_i32 s9, 0x83f
	s_cselect_b64 s[4:5], -1, 0
	s_cmpk_lt_i32 s9, 0x840
	s_waitcnt vmcnt(3)
	v_mov_b64_e32 v[40:41], v[8:9]
	s_cselect_b32 s6, s9, s6
	v_mov_b64_e32 v[38:39], v[6:7]
	v_lshl_add_u32 v6, s6, 3, v28
	v_readlane_b32 s60, v251, 53
	v_add_u32_e32 v8, 0xffffc000, v6
	v_cmp_gt_i32_e32 vcc, s35, v6
	v_readlane_b32 s61, v251, 54
	v_readlane_b32 s63, v251, 56
	s_waitcnt vmcnt(2)
	v_mov_b64_e32 v[36:37], v[12:13]
	v_ashrrev_i32_e32 v7, 31, v6
	v_cndmask_b32_e32 v6, v8, v6, vcc
	v_readlane_b32 s62, v251, 55
	v_mov_b32_e32 v8, s63
	v_mov_b32_e32 v9, s61
	v_mov_b64_e32 v[34:35], v[10:11]
	v_cndmask_b32_e32 v7, 0, v7, vcc
	v_cndmask_b32_e32 v9, v8, v9, vcc
	v_mov_b32_e32 v8, s62
	v_mov_b32_e32 v10, s60
	v_cndmask_b32_e32 v8, v8, v10, vcc
	v_lshlrev_b64 v[6:7], 12, v[6:7]
	v_lshl_add_u64 v[6:7], v[8:9], 0, v[6:7]
	s_waitcnt vmcnt(1)
	v_mov_b64_e32 v[32:33], v[16:17]
	v_lshl_add_u64 v[6:7], v[6:7], 0, v[190:191]
	v_mov_b64_e32 v[30:31], v[14:15]
	global_load_dwordx4 v[18:21], v[6:7], off nt
	global_load_dwordx4 v[14:17], v[6:7], off offset:1024 nt
	global_load_dwordx4 v[10:13], v[6:7], off offset:2048 nt
	s_nop 0
	global_load_dwordx4 v[6:9], v[6:7], off offset:3072 nt
	s_waitcnt vmcnt(4)
	v_mul_f32_e32 v27, v3, v3
	v_mul_f32_e32 v29, v31, v31
	v_fmac_f32_e32 v27, v2, v2
	v_fmac_f32_e32 v29, v30, v30
	v_fmac_f32_e32 v27, v4, v4
	v_fmac_f32_e32 v29, v32, v32
	v_fmac_f32_e32 v27, v5, v5
	v_fmac_f32_e32 v29, v33, v33
	v_add_f32_e32 v27, v27, v29
	v_mul_f32_e32 v29, v35, v35
	v_fmac_f32_e32 v29, v34, v34
	v_fmac_f32_e32 v29, v36, v36
	v_fmac_f32_e32 v29, v37, v37
	v_add_f32_e32 v27, v27, v29
	v_mul_f32_e32 v29, v39, v39
	v_fmac_f32_e32 v29, v38, v38
	v_fmac_f32_e32 v29, v40, v40
	v_fmac_f32_e32 v29, v41, v41
	v_add_f32_e32 v27, v27, v29
	v_and_b32_e32 v29, 64, v244
	v_add_u32_e32 v29, 64, v29
	v_xor_b32_e32 v42, 32, v244
	v_cmp_lt_i32_e32 vcc, v42, v29
	v_cvt_pk_bf16_f32 v2, v2, v3
	v_xor_b32_e32 v3, 4, v244
	v_readlane_b32 s64, v251, 57
	v_cndmask_b32_e32 v42, v244, v42, vcc
	v_lshlrev_b32_e32 v42, 2, v42
	ds_bpermute_b32 v42, v42, v27
	v_readlane_b32 s65, v251, 58
	v_readlane_b32 s66, v251, 59
	v_readlane_b32 s67, v251, 60
	v_readlane_b32 s68, v251, 61
	s_waitcnt lgkmcnt(0)
	v_add_f32_e32 v27, v27, v42
	v_xor_b32_e32 v42, 16, v244
	v_cmp_lt_i32_e32 vcc, v42, v29
	v_readlane_b32 s69, v251, 62
	v_readlane_b32 s70, v251, 63
	v_cndmask_b32_e32 v42, v244, v42, vcc
	v_lshlrev_b32_e32 v42, 2, v42
	ds_bpermute_b32 v42, v42, v27
	v_readlane_b32 s71, v252, 0
	v_readlane_b32 s72, v252, 1
	v_readlane_b32 s73, v252, 2
	v_readlane_b32 s74, v252, 3
	s_waitcnt lgkmcnt(0)
	v_add_f32_e32 v44, v27, v42
	v_xor_b32_e32 v27, 8, v244
	v_cmp_lt_i32_e32 vcc, v27, v29
	v_readlane_b32 s75, v252, 4
	s_nop 0
	v_cndmask_b32_e32 v27, v244, v27, vcc
	v_lshlrev_b32_e32 v27, 2, v27
	ds_bpermute_b32 v45, v27, v44
	v_cmp_lt_i32_e32 vcc, v3, v29
	v_ashrrev_i32_e32 v27, 31, v26
	v_lshlrev_b64 v[42:43], 11, v[26:27]
	v_cndmask_b32_e32 v3, v244, v3, vcc
	s_waitcnt lgkmcnt(0)
	v_add_f32_e32 v44, v44, v45
	v_lshlrev_b32_e32 v3, 2, v3
	ds_bpermute_b32 v45, v3, v44
	v_cvt_pk_bf16_f32 v3, v4, v5
	v_lshl_add_u64 v[4:5], v[22:23], 0, v[42:43]
	global_store_dwordx2 v[4:5], v[2:3], off
	v_xor_b32_e32 v3, 2, v244
	v_cmp_lt_i32_e32 vcc, v3, v29
	s_waitcnt lgkmcnt(0)
	v_add_f32_e32 v42, v44, v45
	v_cvt_pk_bf16_f32 v2, v30, v31
	v_cvt_pk_bf16_f32 v30, v34, v35
	v_cvt_pk_bf16_f32 v31, v36, v37
	global_store_dwordx2 v[4:5], v[30:31], off offset:1024
	v_cndmask_b32_e32 v3, v244, v3, vcc
	v_lshlrev_b32_e32 v3, 2, v3
	ds_bpermute_b32 v43, v3, v42
	v_cvt_pk_bf16_f32 v3, v32, v33
	global_store_dwordx2 v[4:5], v[2:3], off offset:512
	v_xor_b32_e32 v3, 1, v244
	v_cmp_lt_i32_e32 vcc, v3, v29
	s_waitcnt lgkmcnt(0)
	v_add_f32_e32 v2, v42, v43
	v_cvt_pk_bf16_f32 v30, v38, v39
	v_cvt_pk_bf16_f32 v31, v40, v41
	global_store_dwordx2 v[4:5], v[30:31], off offset:1536
	v_cndmask_b32_e32 v3, v244, v3, vcc
	v_lshlrev_b32_e32 v3, 2, v3
	ds_bpermute_b32 v3, v3, v2
	s_and_saveexec_b64 s[6:7], s[0:1]
	s_cbranch_execz .LBB0_1340
	s_waitcnt lgkmcnt(0)
	v_add_f32_e32 v2, v2, v3
	v_cndmask_b32_e64 v4, 0, v2, s[2:3]
	v_lshlrev_b64 v[2:3], 6, v[26:27]
	v_lshl_add_u64 v[2:3], v[24:25], 0, v[2:3]
	global_store_dword v[2:3], v4, off
	s_branch .LBB0_1340
